# P0 weight copies hand-written: LDS-DMA loads two blocks deep per wave, swizzled LDS image, on v43
# baseline (speedup 1.0000x reference)
; #define LAS __attribute__((address_space(3)))
; __device__ __forceinline__ unsigned pk2(float lo, float hi) { return pg8::cvt_pk_bf16(lo, hi); }
; #define LDS_WAIT() asm volatile("s_waitcnt lgkmcnt(0)" ::: "memory")
; __device__ __forceinline__ void transpose_item(const float* W, int K, int N, bf16_t* WT, LAS float* scr, int item, int lane) {
;     const int nblk = (N + 31) / 32, kb = item / nblk, nb = item % nblk, k0 = 64 * kb, n0 = 32 * nb;
;     const int nn = n0 + (lane & 31); const bool ok = nn < N;
;     float v[32];
; #pragma unroll
;     for (int i = 0; i < 32; ++i) { const int kk = 2 * i + (lane >> 5); v[i] = ok ? W[(size_t)(k0 + kk) * N + nn] : 0.f; }
; #pragma unroll
;     for (int i = 0; i < 32; ++i) { const int kk = 2 * i + (lane >> 5); scr[kk * 33 + (lane & 31)] = v[i]; }
;     LDS_WAIT(); asm volatile("" ::: "memory");
;     const int c = lane & 7;
; #pragma unroll
;     for (int j = 0; j < 4; ++j) { const int n = (lane >> 3) + 8 * j; const LAS float* s = scr + (8 * c) * 33 + n;
;         u32x4 o; o.x = pk2(s[0 * 33], s[1 * 33]); o.y = pk2(s[2 * 33], s[3 * 33]); o.z = pk2(s[4 * 33], s[5 * 33]); o.w = pk2(s[6 * 33], s[7 * 33]);
;         *(u32x4*)(WT + (size_t)(n0 + n) * K + k0 + 8 * c) = o; }
;     LDS_WAIT(); asm volatile("" ::: "memory");
; }
; __global__ void __launch_bounds__(512, 2) mega(Args a) {
;     ...
;         for (int it = gw; it < 4 * I_ADA; it += NGW) { const int l = it / I_ADA, r = it - l * I_ADA;
;             transpose_item(((const float*)ap->in[8]) + (size_t)l * DM * 3 * DM, DM, 3 * DM, WSP(bf16_t, WS_WADA) + (size_t)l * 3 * DM * DM, scr, r, lane); }
.LBB0_5:
	s_or_b64 exec, exec, s[6:7]
	s_mov_b32 s6, -1
	s_andn2_b32 s3, s3, 63
	v_mbcnt_lo_u32_b32 v2, s6, 0
	v_mbcnt_hi_u32_b32 v2, s6, v2
	v_or_b32_e32 v12, s3, v2
	s_mov_b32 s13, s2
	s_mov_b64 s[6:7], s[0:1]
	s_lshl_b32 s9, s13, 3
	v_mov_b64_e32 v[2:3], s[6:7]
	flat_load_dwordx2 v[6:7], v[2:3] offset:152
	v_readfirstlane_b32 s8, v12
	s_ashr_i32 s8, s8, 6
	s_add_i32 s14, s8, s9
	s_cmpk_gt_i32 s14, 0x5fff
	s_cbranch_scc1 .LBB0_72
	s_load_dwordx2 s[16:17], s[0:1], 0x40
	s_lshl_b32 s10, s8, 14
	v_and_b32_e32 v18, 63, v12
	v_and_b32_e32 v19, 31, v18
	v_lshrrev_b32_e32 v20, 5, v18
	v_xor_b32_e32 v2, 0, v19
	v_lshlrev_b32_e32 v2, 2, v2
	v_mov_b32_e32 v21, 0x6000
	v_mad_u32_u24 v2, v20, v21, v2
	v_xor_b32_e32 v3, 8, v19
	v_lshlrev_b32_e32 v3, 2, v3
	v_mov_b32_e32 v21, 0x6000
	v_mad_u32_u24 v3, v20, v21, v3
	v_xor_b32_e32 v4, 16, v19
	v_lshlrev_b32_e32 v4, 2, v4
	v_mov_b32_e32 v21, 0x6000
	v_mad_u32_u24 v4, v20, v21, v4
	v_xor_b32_e32 v5, 24, v19
	v_lshlrev_b32_e32 v5, 2, v5
	v_mov_b32_e32 v21, 0x6000
	v_mad_u32_u24 v5, v20, v21, v5
	v_and_b32_e32 v19, 7, v18
	v_lshrrev_b32_e32 v20, 3, v18
	v_and_b32_e32 v21, 3, v19
	v_lshlrev_b32_e32 v22, 10, v19
	v_lshl_add_u32 v22, s8, 14, v22
	v_xor_b32_e32 v23, 0, v21
	v_lshl_add_u32 v23, v23, 3, v20
	v_lshl_add_u32 v8, v23, 2, v22
	v_xor_b32_e32 v23, 1, v21
	v_lshl_add_u32 v23, v23, 3, v20
	v_lshl_add_u32 v9, v23, 2, v22
	v_xor_b32_e32 v23, 2, v21
	v_lshl_add_u32 v23, v23, 3, v20
	v_lshl_add_u32 v10, v23, 2, v22
	v_xor_b32_e32 v23, 3, v21
	v_lshl_add_u32 v23, v23, 3, v20
	v_lshl_add_u32 v11, v23, 2, v22
	v_lshlrev_b32_e32 v23, 12, v20
	v_lshl_add_u32 v13, v19, 4, v23
	v_add_u32_e32 v14, 0x8000, v13
	v_add_u32_e32 v15, 0x10000, v13
	v_add_u32_e32 v16, 0x18000, v13
	s_mov_b32 s8, s14
	s_waitcnt vmcnt(0) lgkmcnt(0)
	v_readfirstlane_b32 s18, v6
	v_readfirstlane_b32 s19, v7
	s_nop 0
	s_add_u32 s18, s18, 0xa200000
	s_addc_u32 s19, s19, 0
	s_mov_b32 s11, s8
	s_mul_hi_u32 s100, s11, 0xaaaab
	s_mul_i32 vcc_lo, s100, 0x1800
	s_sub_u32 s11, s11, vcc_lo
	s_mul_hi_u32 s101, s11, 0x1555556
	s_mul_i32 vcc_lo, s101, 0xc0
	s_sub_u32 s11, s11, vcc_lo
	s_mul_i32 vcc_lo, s100, 0x3000000
	s_mul_i32 vcc_hi, s101, 0x180000
	s_add_u32 vcc_lo, vcc_lo, vcc_hi
	s_lshl_b32 vcc_hi, s11, 7
	s_add_u32 vcc_lo, vcc_lo, vcc_hi
	s_add_u32 s14, s16, vcc_lo
	s_addc_u32 s15, s17, 0
	s_mov_b32 m0, s10
	s_nop 0
	global_load_lds_dword v2, s[14:15]
	s_add_i32 m0, m0, 0x100
	s_add_u32 s14, s14, 0xc000
	s_addc_u32 s15, s15, 0
	global_load_lds_dword v2, s[14:15]
	s_add_i32 m0, m0, 0x100
	s_add_u32 s14, s14, 0xc000
	s_addc_u32 s15, s15, 0
	global_load_lds_dword v2, s[14:15]
	s_add_i32 m0, m0, 0x100
	s_add_u32 s14, s14, 0xc000
	s_addc_u32 s15, s15, 0
	global_load_lds_dword v2, s[14:15]
	s_add_i32 m0, m0, 0x100
	s_add_u32 s14, s14, 0xc000
	s_addc_u32 s15, s15, 0
	global_load_lds_dword v3, s[14:15]
	s_add_i32 m0, m0, 0x100
	s_add_u32 s14, s14, 0xc000
	s_addc_u32 s15, s15, 0
	global_load_lds_dword v3, s[14:15]
	s_add_i32 m0, m0, 0x100
	s_add_u32 s14, s14, 0xc000
	s_addc_u32 s15, s15, 0
	global_load_lds_dword v3, s[14:15]
	s_add_i32 m0, m0, 0x100
	s_add_u32 s14, s14, 0xc000
	s_addc_u32 s15, s15, 0
	global_load_lds_dword v3, s[14:15]
	s_add_i32 m0, m0, 0x100
	s_add_u32 s14, s14, 0xc000
	s_addc_u32 s15, s15, 0
	global_load_lds_dword v4, s[14:15]
	s_add_i32 m0, m0, 0x100
	s_add_u32 s14, s14, 0xc000
	s_addc_u32 s15, s15, 0
	global_load_lds_dword v4, s[14:15]
	s_add_i32 m0, m0, 0x100
	s_add_u32 s14, s14, 0xc000
	s_addc_u32 s15, s15, 0
	global_load_lds_dword v4, s[14:15]
	s_add_i32 m0, m0, 0x100
	s_add_u32 s14, s14, 0xc000
	s_addc_u32 s15, s15, 0
	global_load_lds_dword v4, s[14:15]
	s_add_i32 m0, m0, 0x100
	s_add_u32 s14, s14, 0xc000
	s_addc_u32 s15, s15, 0
	global_load_lds_dword v5, s[14:15]
	s_add_i32 m0, m0, 0x100
	s_add_u32 s14, s14, 0xc000
	s_addc_u32 s15, s15, 0
	global_load_lds_dword v5, s[14:15]
	s_add_i32 m0, m0, 0x100
	s_add_u32 s14, s14, 0xc000
	s_addc_u32 s15, s15, 0
	global_load_lds_dword v5, s[14:15]
	s_add_i32 m0, m0, 0x100
	s_add_u32 s14, s14, 0xc000
	s_addc_u32 s15, s15, 0
	global_load_lds_dword v5, s[14:15]
	s_add_i32 m0, m0, 0x100
	s_add_u32 s14, s14, 0xc000
	s_addc_u32 s15, s15, 0
	global_load_lds_dword v2, s[14:15]
	s_add_i32 m0, m0, 0x100
	s_add_u32 s14, s14, 0xc000
	s_addc_u32 s15, s15, 0
	global_load_lds_dword v2, s[14:15]
	s_add_i32 m0, m0, 0x100
	s_add_u32 s14, s14, 0xc000
	s_addc_u32 s15, s15, 0
	global_load_lds_dword v2, s[14:15]
	s_add_i32 m0, m0, 0x100
	s_add_u32 s14, s14, 0xc000
	s_addc_u32 s15, s15, 0
	global_load_lds_dword v2, s[14:15]
	s_add_i32 m0, m0, 0x100
	s_add_u32 s14, s14, 0xc000
	s_addc_u32 s15, s15, 0
	global_load_lds_dword v3, s[14:15]
	s_add_i32 m0, m0, 0x100
	s_add_u32 s14, s14, 0xc000
	s_addc_u32 s15, s15, 0
	global_load_lds_dword v3, s[14:15]
	s_add_i32 m0, m0, 0x100
	s_add_u32 s14, s14, 0xc000
	s_addc_u32 s15, s15, 0
	global_load_lds_dword v3, s[14:15]
	s_add_i32 m0, m0, 0x100
	s_add_u32 s14, s14, 0xc000
	s_addc_u32 s15, s15, 0
	global_load_lds_dword v3, s[14:15]
	s_add_i32 m0, m0, 0x100
	s_add_u32 s14, s14, 0xc000
	s_addc_u32 s15, s15, 0
	global_load_lds_dword v4, s[14:15]
	s_add_i32 m0, m0, 0x100
	s_add_u32 s14, s14, 0xc000
	s_addc_u32 s15, s15, 0
	global_load_lds_dword v4, s[14:15]
	s_add_i32 m0, m0, 0x100
	s_add_u32 s14, s14, 0xc000
	s_addc_u32 s15, s15, 0
	global_load_lds_dword v4, s[14:15]
	s_add_i32 m0, m0, 0x100
	s_add_u32 s14, s14, 0xc000
	s_addc_u32 s15, s15, 0
	global_load_lds_dword v4, s[14:15]
	s_add_i32 m0, m0, 0x100
	s_add_u32 s14, s14, 0xc000
	s_addc_u32 s15, s15, 0
	global_load_lds_dword v5, s[14:15]
	s_add_i32 m0, m0, 0x100
	s_add_u32 s14, s14, 0xc000
	s_addc_u32 s15, s15, 0
	global_load_lds_dword v5, s[14:15]
	s_add_i32 m0, m0, 0x100
	s_add_u32 s14, s14, 0xc000
	s_addc_u32 s15, s15, 0
	global_load_lds_dword v5, s[14:15]
	s_add_i32 m0, m0, 0x100
	s_add_u32 s14, s14, 0xc000
	s_addc_u32 s15, s15, 0
	global_load_lds_dword v5, s[14:15]
	s_add_i32 s9, s8, 0x800
	s_cmpk_lt_i32 s9, 0x6000
	s_cbranch_scc0 .Lp0a_nopf1
; #define LAS __attribute__((address_space(3)))
; __device__ __forceinline__ unsigned pk2(float lo, float hi) { return pg8::cvt_pk_bf16(lo, hi); }
; #define LDS_WAIT() asm volatile("s_waitcnt lgkmcnt(0)" ::: "memory")
; __device__ __forceinline__ void transpose_item(const float* W, int K, int N, bf16_t* WT, LAS float* scr, int item, int lane) {
;     const int nblk = (N + 31) / 32, kb = item / nblk, nb = item % nblk, k0 = 64 * kb, n0 = 32 * nb;
;     const int nn = n0 + (lane & 31); const bool ok = nn < N;
;     float v[32];
; #pragma unroll
;     for (int i = 0; i < 32; ++i) { const int kk = 2 * i + (lane >> 5); v[i] = ok ? W[(size_t)(k0 + kk) * N + nn] : 0.f; }
; #pragma unroll
;     for (int i = 0; i < 32; ++i) { const int kk = 2 * i + (lane >> 5); scr[kk * 33 + (lane & 31)] = v[i]; }
;     LDS_WAIT(); asm volatile("" ::: "memory");
;     const int c = lane & 7;
; #pragma unroll
;     for (int j = 0; j < 4; ++j) { const int n = (lane >> 3) + 8 * j; const LAS float* s = scr + (8 * c) * 33 + n;
;         u32x4 o; o.x = pk2(s[0 * 33], s[1 * 33]); o.y = pk2(s[2 * 33], s[3 * 33]); o.z = pk2(s[4 * 33], s[5 * 33]); o.w = pk2(s[6 * 33], s[7 * 33]);
;         *(u32x4*)(WT + (size_t)(n0 + n) * K + k0 + 8 * c) = o; }
; __global__ void __launch_bounds__(512, 2) mega(Args a) {
;     ...
;         for (int it = gw; it < 4 * I_ADA; it += NGW) { const int l = it / I_ADA, r = it - l * I_ADA;
;             transpose_item(((const float*)ap->in[8]) + (size_t)l * DM * 3 * DM, DM, 3 * DM, WSP(bf16_t, WS_WADA) + (size_t)l * 3 * DM * DM, scr, r, lane); }
	s_mov_b32 s11, s9
	s_mul_hi_u32 s100, s11, 0xaaaab
	s_mul_i32 vcc_lo, s100, 0x1800
	s_sub_u32 s11, s11, vcc_lo
	s_mul_hi_u32 s101, s11, 0x1555556
	s_mul_i32 vcc_lo, s101, 0xc0
	s_sub_u32 s11, s11, vcc_lo
	s_mul_i32 vcc_lo, s100, 0x3000000
	s_mul_i32 vcc_hi, s101, 0x180000
	s_add_u32 vcc_lo, vcc_lo, vcc_hi
	s_lshl_b32 vcc_hi, s11, 7
	s_add_u32 vcc_lo, vcc_lo, vcc_hi
	s_add_u32 s14, s16, vcc_lo
	s_addc_u32 s15, s17, 0
	s_xor_b32 m0, s10, 0x2000
	s_nop 0
	global_load_lds_dword v2, s[14:15]
	s_add_i32 m0, m0, 0x100
	s_add_u32 s14, s14, 0xc000
	s_addc_u32 s15, s15, 0
	global_load_lds_dword v2, s[14:15]
	s_add_i32 m0, m0, 0x100
	s_add_u32 s14, s14, 0xc000
	s_addc_u32 s15, s15, 0
	global_load_lds_dword v2, s[14:15]
	s_add_i32 m0, m0, 0x100
	s_add_u32 s14, s14, 0xc000
	s_addc_u32 s15, s15, 0
	global_load_lds_dword v2, s[14:15]
	s_add_i32 m0, m0, 0x100
	s_add_u32 s14, s14, 0xc000
	s_addc_u32 s15, s15, 0
	global_load_lds_dword v3, s[14:15]
	s_add_i32 m0, m0, 0x100
	s_add_u32 s14, s14, 0xc000
	s_addc_u32 s15, s15, 0
	global_load_lds_dword v3, s[14:15]
	s_add_i32 m0, m0, 0x100
	s_add_u32 s14, s14, 0xc000
	s_addc_u32 s15, s15, 0
	global_load_lds_dword v3, s[14:15]
	s_add_i32 m0, m0, 0x100
	s_add_u32 s14, s14, 0xc000
	s_addc_u32 s15, s15, 0
	global_load_lds_dword v3, s[14:15]
	s_add_i32 m0, m0, 0x100
	s_add_u32 s14, s14, 0xc000
	s_addc_u32 s15, s15, 0
	global_load_lds_dword v4, s[14:15]
	s_add_i32 m0, m0, 0x100
	s_add_u32 s14, s14, 0xc000
	s_addc_u32 s15, s15, 0
	global_load_lds_dword v4, s[14:15]
	s_add_i32 m0, m0, 0x100
	s_add_u32 s14, s14, 0xc000
	s_addc_u32 s15, s15, 0
	global_load_lds_dword v4, s[14:15]
	s_add_i32 m0, m0, 0x100
	s_add_u32 s14, s14, 0xc000
	s_addc_u32 s15, s15, 0
	global_load_lds_dword v4, s[14:15]
	s_add_i32 m0, m0, 0x100
	s_add_u32 s14, s14, 0xc000
	s_addc_u32 s15, s15, 0
	global_load_lds_dword v5, s[14:15]
	s_add_i32 m0, m0, 0x100
	s_add_u32 s14, s14, 0xc000
	s_addc_u32 s15, s15, 0
	global_load_lds_dword v5, s[14:15]
	s_add_i32 m0, m0, 0x100
	s_add_u32 s14, s14, 0xc000
	s_addc_u32 s15, s15, 0
	global_load_lds_dword v5, s[14:15]
	s_add_i32 m0, m0, 0x100
	s_add_u32 s14, s14, 0xc000
	s_addc_u32 s15, s15, 0
	global_load_lds_dword v5, s[14:15]
	s_add_i32 m0, m0, 0x100
	s_add_u32 s14, s14, 0xc000
	s_addc_u32 s15, s15, 0
	global_load_lds_dword v2, s[14:15]
	s_add_i32 m0, m0, 0x100
	s_add_u32 s14, s14, 0xc000
	s_addc_u32 s15, s15, 0
	global_load_lds_dword v2, s[14:15]
	s_add_i32 m0, m0, 0x100
	s_add_u32 s14, s14, 0xc000
	s_addc_u32 s15, s15, 0
	global_load_lds_dword v2, s[14:15]
	s_add_i32 m0, m0, 0x100
	s_add_u32 s14, s14, 0xc000
	s_addc_u32 s15, s15, 0
	global_load_lds_dword v2, s[14:15]
	s_add_i32 m0, m0, 0x100
	s_add_u32 s14, s14, 0xc000
	s_addc_u32 s15, s15, 0
	global_load_lds_dword v3, s[14:15]
	s_add_i32 m0, m0, 0x100
	s_add_u32 s14, s14, 0xc000
	s_addc_u32 s15, s15, 0
	global_load_lds_dword v3, s[14:15]
	s_add_i32 m0, m0, 0x100
	s_add_u32 s14, s14, 0xc000
	s_addc_u32 s15, s15, 0
	global_load_lds_dword v3, s[14:15]
	s_add_i32 m0, m0, 0x100
	s_add_u32 s14, s14, 0xc000
	s_addc_u32 s15, s15, 0
	global_load_lds_dword v3, s[14:15]
	s_add_i32 m0, m0, 0x100
	s_add_u32 s14, s14, 0xc000
	s_addc_u32 s15, s15, 0
	global_load_lds_dword v4, s[14:15]
	s_add_i32 m0, m0, 0x100
	s_add_u32 s14, s14, 0xc000
	s_addc_u32 s15, s15, 0
	global_load_lds_dword v4, s[14:15]
	s_add_i32 m0, m0, 0x100
	s_add_u32 s14, s14, 0xc000
	s_addc_u32 s15, s15, 0
	global_load_lds_dword v4, s[14:15]
	s_add_i32 m0, m0, 0x100
	s_add_u32 s14, s14, 0xc000
	s_addc_u32 s15, s15, 0
	global_load_lds_dword v4, s[14:15]
	s_add_i32 m0, m0, 0x100
	s_add_u32 s14, s14, 0xc000
	s_addc_u32 s15, s15, 0
	global_load_lds_dword v5, s[14:15]
	s_add_i32 m0, m0, 0x100
	s_add_u32 s14, s14, 0xc000
	s_addc_u32 s15, s15, 0
	global_load_lds_dword v5, s[14:15]
	s_add_i32 m0, m0, 0x100
	s_add_u32 s14, s14, 0xc000
	s_addc_u32 s15, s15, 0
	global_load_lds_dword v5, s[14:15]
	s_add_i32 m0, m0, 0x100
	s_add_u32 s14, s14, 0xc000
	s_addc_u32 s15, s15, 0
	global_load_lds_dword v5, s[14:15]
.Lp0a_nopf1:
	s_addk_i32 s9, 0x800
.Lp0a_loop:
	s_mov_b32 s11, s8
	s_mul_hi_u32 s100, s11, 0xaaaab
	s_mul_i32 vcc_lo, s100, 0x1800
	s_sub_u32 s11, s11, vcc_lo
	s_mul_hi_u32 s101, s11, 0x1555556
	s_mul_i32 vcc_lo, s101, 0xc0
	s_sub_u32 s11, s11, vcc_lo
	s_mul_i32 vcc_lo, s100, 0x1800000
	s_lshl_b32 vcc_hi, s11, 17
	s_add_u32 vcc_lo, vcc_lo, vcc_hi
	s_lshl_b32 vcc_hi, s101, 7
	s_add_u32 vcc_lo, vcc_lo, vcc_hi
	s_add_u32 s98, s18, vcc_lo
	s_addc_u32 s99, s19, 0
	s_add_i32 vcc_lo, s8, 0x800
	s_cmpk_lt_i32 vcc_lo, 0x6000
	s_cbranch_scc1 .Lp0a_w32
	s_waitcnt vmcnt(0)
	s_branch .Lp0a_wd
.Lp0a_w32:
	s_waitcnt vmcnt(32)
; #define LAS __attribute__((address_space(3)))
; __device__ __forceinline__ unsigned pk2(float lo, float hi) { return pg8::cvt_pk_bf16(lo, hi); }
; #define LDS_WAIT() asm volatile("s_waitcnt lgkmcnt(0)" ::: "memory")
; __device__ __forceinline__ void transpose_item(const float* W, int K, int N, bf16_t* WT, LAS float* scr, int item, int lane) {
;     ...
;     const int c = lane & 7;
; #pragma unroll
;     for (int j = 0; j < 4; ++j) { const int n = (lane >> 3) + 8 * j; const LAS float* s = scr + (8 * c) * 33 + n;
;         u32x4 o; o.x = pk2(s[0 * 33], s[1 * 33]); o.y = pk2(s[2 * 33], s[3 * 33]); o.z = pk2(s[4 * 33], s[5 * 33]); o.w = pk2(s[6 * 33], s[7 * 33]);
;         *(u32x4*)(WT + (size_t)(n0 + n) * K + k0 + 8 * c) = o; }
;     LDS_WAIT(); asm volatile("" ::: "memory");
; }
.Lp0a_wd:
	ds_read2_b32 v[18:19], v8 offset0:0 offset1:32
	ds_read2_b32 v[20:21], v8 offset0:64 offset1:96
	ds_read2_b32 v[22:23], v8 offset0:128 offset1:160
	ds_read2_b32 v[24:25], v8 offset0:192 offset1:224
	ds_read2_b32 v[26:27], v9 offset0:0 offset1:32
	ds_read2_b32 v[28:29], v9 offset0:64 offset1:96
	ds_read2_b32 v[30:31], v9 offset0:128 offset1:160
	ds_read2_b32 v[32:33], v9 offset0:192 offset1:224
	ds_read2_b32 v[34:35], v10 offset0:0 offset1:32
	ds_read2_b32 v[36:37], v10 offset0:64 offset1:96
	ds_read2_b32 v[38:39], v10 offset0:128 offset1:160
	ds_read2_b32 v[40:41], v10 offset0:192 offset1:224
	ds_read2_b32 v[42:43], v11 offset0:0 offset1:32
	ds_read2_b32 v[44:45], v11 offset0:64 offset1:96
	ds_read2_b32 v[46:47], v11 offset0:128 offset1:160
	ds_read2_b32 v[48:49], v11 offset0:192 offset1:224
	s_waitcnt lgkmcnt(12)
	v_cvt_pk_bf16_f32 v50, v18, v19
	v_cvt_pk_bf16_f32 v51, v20, v21
	v_cvt_pk_bf16_f32 v52, v22, v23
	v_cvt_pk_bf16_f32 v53, v24, v25
	global_store_dwordx4 v13, v[50:53], s[98:99]
	s_waitcnt lgkmcnt(8)
	v_cvt_pk_bf16_f32 v54, v26, v27
	v_cvt_pk_bf16_f32 v55, v28, v29
	v_cvt_pk_bf16_f32 v56, v30, v31
	v_cvt_pk_bf16_f32 v57, v32, v33
	global_store_dwordx4 v14, v[54:57], s[98:99]
	s_waitcnt lgkmcnt(4)
	v_cvt_pk_bf16_f32 v50, v34, v35
	v_cvt_pk_bf16_f32 v51, v36, v37
	v_cvt_pk_bf16_f32 v52, v38, v39
	v_cvt_pk_bf16_f32 v53, v40, v41
	global_store_dwordx4 v15, v[50:53], s[98:99]
	s_waitcnt lgkmcnt(0)
	v_cvt_pk_bf16_f32 v54, v42, v43
	v_cvt_pk_bf16_f32 v55, v44, v45
	v_cvt_pk_bf16_f32 v56, v46, v47
	v_cvt_pk_bf16_f32 v57, v48, v49
	global_store_dwordx4 v16, v[54:57], s[98:99]
	s_cmpk_lt_i32 s9, 0x6000
	s_cbranch_scc0 .Lp0a_nopf
	s_mov_b32 s11, s9
	s_mul_hi_u32 s100, s11, 0xaaaab
	s_mul_i32 vcc_lo, s100, 0x1800
	s_sub_u32 s11, s11, vcc_lo
	s_mul_hi_u32 s101, s11, 0x1555556
	s_mul_i32 vcc_lo, s101, 0xc0
	s_sub_u32 s11, s11, vcc_lo
	s_mul_i32 vcc_lo, s100, 0x3000000
	s_mul_i32 vcc_hi, s101, 0x180000
	s_add_u32 vcc_lo, vcc_lo, vcc_hi
	s_lshl_b32 vcc_hi, s11, 7
	s_add_u32 vcc_lo, vcc_lo, vcc_hi
	s_add_u32 s14, s16, vcc_lo
	s_addc_u32 s15, s17, 0
	s_mov_b32 m0, s10
	s_nop 0
	global_load_lds_dword v2, s[14:15]
	s_add_i32 m0, m0, 0x100
	s_add_u32 s14, s14, 0xc000
	s_addc_u32 s15, s15, 0
	global_load_lds_dword v2, s[14:15]
	s_add_i32 m0, m0, 0x100
	s_add_u32 s14, s14, 0xc000
	s_addc_u32 s15, s15, 0
	global_load_lds_dword v2, s[14:15]
	s_add_i32 m0, m0, 0x100
	s_add_u32 s14, s14, 0xc000
	s_addc_u32 s15, s15, 0
	global_load_lds_dword v2, s[14:15]
	s_add_i32 m0, m0, 0x100
	s_add_u32 s14, s14, 0xc000
	s_addc_u32 s15, s15, 0
	global_load_lds_dword v3, s[14:15]
	s_add_i32 m0, m0, 0x100
	s_add_u32 s14, s14, 0xc000
	s_addc_u32 s15, s15, 0
	global_load_lds_dword v3, s[14:15]
	s_add_i32 m0, m0, 0x100
	s_add_u32 s14, s14, 0xc000
	s_addc_u32 s15, s15, 0
	global_load_lds_dword v3, s[14:15]
	s_add_i32 m0, m0, 0x100
	s_add_u32 s14, s14, 0xc000
	s_addc_u32 s15, s15, 0
	global_load_lds_dword v3, s[14:15]
	s_add_i32 m0, m0, 0x100
	s_add_u32 s14, s14, 0xc000
	s_addc_u32 s15, s15, 0
	global_load_lds_dword v4, s[14:15]
	s_add_i32 m0, m0, 0x100
	s_add_u32 s14, s14, 0xc000
	s_addc_u32 s15, s15, 0
	global_load_lds_dword v4, s[14:15]
	s_add_i32 m0, m0, 0x100
	s_add_u32 s14, s14, 0xc000
	s_addc_u32 s15, s15, 0
	global_load_lds_dword v4, s[14:15]
	s_add_i32 m0, m0, 0x100
	s_add_u32 s14, s14, 0xc000
	s_addc_u32 s15, s15, 0
	global_load_lds_dword v4, s[14:15]
	s_add_i32 m0, m0, 0x100
	s_add_u32 s14, s14, 0xc000
	s_addc_u32 s15, s15, 0
	global_load_lds_dword v5, s[14:15]
	s_add_i32 m0, m0, 0x100
	s_add_u32 s14, s14, 0xc000
	s_addc_u32 s15, s15, 0
	global_load_lds_dword v5, s[14:15]
	s_add_i32 m0, m0, 0x100
	s_add_u32 s14, s14, 0xc000
	s_addc_u32 s15, s15, 0
	global_load_lds_dword v5, s[14:15]
	s_add_i32 m0, m0, 0x100
	s_add_u32 s14, s14, 0xc000
	s_addc_u32 s15, s15, 0
	global_load_lds_dword v5, s[14:15]
	s_add_i32 m0, m0, 0x100
	s_add_u32 s14, s14, 0xc000
	s_addc_u32 s15, s15, 0
	global_load_lds_dword v2, s[14:15]
	s_add_i32 m0, m0, 0x100
	s_add_u32 s14, s14, 0xc000
	s_addc_u32 s15, s15, 0
	global_load_lds_dword v2, s[14:15]
	s_add_i32 m0, m0, 0x100
	s_add_u32 s14, s14, 0xc000
	s_addc_u32 s15, s15, 0
	global_load_lds_dword v2, s[14:15]
	s_add_i32 m0, m0, 0x100
	s_add_u32 s14, s14, 0xc000
	s_addc_u32 s15, s15, 0
	global_load_lds_dword v2, s[14:15]
	s_add_i32 m0, m0, 0x100
	s_add_u32 s14, s14, 0xc000
	s_addc_u32 s15, s15, 0
	global_load_lds_dword v3, s[14:15]
	s_add_i32 m0, m0, 0x100
	s_add_u32 s14, s14, 0xc000
	s_addc_u32 s15, s15, 0
	global_load_lds_dword v3, s[14:15]
	s_add_i32 m0, m0, 0x100
	s_add_u32 s14, s14, 0xc000
	s_addc_u32 s15, s15, 0
	global_load_lds_dword v3, s[14:15]
	s_add_i32 m0, m0, 0x100
	s_add_u32 s14, s14, 0xc000
	s_addc_u32 s15, s15, 0
	global_load_lds_dword v3, s[14:15]
	s_add_i32 m0, m0, 0x100
	s_add_u32 s14, s14, 0xc000
	s_addc_u32 s15, s15, 0
	global_load_lds_dword v4, s[14:15]
	s_add_i32 m0, m0, 0x100
	s_add_u32 s14, s14, 0xc000
	s_addc_u32 s15, s15, 0
	global_load_lds_dword v4, s[14:15]
	s_add_i32 m0, m0, 0x100
	s_add_u32 s14, s14, 0xc000
	s_addc_u32 s15, s15, 0
	global_load_lds_dword v4, s[14:15]
	s_add_i32 m0, m0, 0x100
	s_add_u32 s14, s14, 0xc000
	s_addc_u32 s15, s15, 0
	global_load_lds_dword v4, s[14:15]
	s_add_i32 m0, m0, 0x100
	s_add_u32 s14, s14, 0xc000
	s_addc_u32 s15, s15, 0
	global_load_lds_dword v5, s[14:15]
	s_add_i32 m0, m0, 0x100
	s_add_u32 s14, s14, 0xc000
	s_addc_u32 s15, s15, 0
	global_load_lds_dword v5, s[14:15]
	s_add_i32 m0, m0, 0x100
	s_add_u32 s14, s14, 0xc000
	s_addc_u32 s15, s15, 0
	global_load_lds_dword v5, s[14:15]
	s_add_i32 m0, m0, 0x100
	s_add_u32 s14, s14, 0xc000
	s_addc_u32 s15, s15, 0
	global_load_lds_dword v5, s[14:15]
.Lp0a_nopf:
	s_addk_i32 s9, 0x800
	s_addk_i32 s8, 0x800
	s_xor_b32 s10, s10, 0x2000
	v_xor_b32_e32 v8, 0x2000, v8
	v_xor_b32_e32 v9, 0x2000, v9
	v_xor_b32_e32 v10, 0x2000, v10
	v_xor_b32_e32 v11, 0x2000, v11
	s_cmpk_lt_i32 s8, 0x6000
	s_cbranch_scc1 .Lp0a_loop
	s_waitcnt vmcnt(0)

; #define LAS __attribute__((address_space(3)))
; __device__ __forceinline__ void transpose_item(const float* W, int K, int N, bf16_t* WT, LAS float* scr, int item, int lane) {
;     const int nblk = (N + 31) / 32, kb = item / nblk, nb = item % nblk, k0 = 64 * kb, n0 = 32 * nb;
;     const int nn = n0 + (lane & 31); const bool ok = nn < N;
;     float v[32];
; #pragma unroll
;     for (int i = 0; i < 32; ++i) { const int kk = 2 * i + (lane >> 5); v[i] = ok ? W[(size_t)(k0 + kk) * N + nn] : 0.f; }
; #pragma unroll
;     for (int i = 0; i < 32; ++i) { const int kk = 2 * i + (lane >> 5); scr[kk * 33 + (lane & 31)] = v[i]; }
; __global__ void __launch_bounds__(512, 2) mega(Args a) {
;     ...
;         LAS float* scr = (LAS float*)(lds + wave * 16384);
;         const int it0 = bx < NGEMM ? N1 + bx * 8 + wave : (bx - NGEMM) * 8 + wave, itN = bx < NGEMM ? NIT2 : N1, its = bx < NGEMM ? NGEMM * 8 : (G - NGEMM) * 8;
; #pragma unroll 1
;         for (int it = it0; it < itN; it += its) {
;             int r = it;
;             if (r < 4 * I_IN) { const int l = r / I_IN; r -= l * I_IN; transpose_item(((const float*)ap->in[10]) + (size_t)l * DM * DIN, DM, DIN, WSP(bf16_t, WS_WIN) + (size_t)l * DINP * DM, scr, r, lane); }
;             else { r -= 4 * I_IN; const int l = r / I_OUT; r -= l * I_OUT; transpose_item(((const float*)ap->in[16]) + (size_t)l * DM * DM, DM, DM, WSP(bf16_t, WS_WOUT) + (size_t)l * DM * DM, scr, r, lane); }
;         }
.LBB0_150:
	s_ashr_i32 s5, s33, 6
	s_lshl_b32 s8, s13, 3
	s_add_i32 s8, s5, s8
	s_add_i32 s13, s8, s4
	s_cmp_ge_i32 s13, s14
	s_cbranch_scc1 .LBB0_221
	s_load_dwordx2 s[16:17], s[0:1], 0x50
	s_load_dwordx2 s[18:19], s[0:1], 0x80
	s_lshl_b32 s10, s5, 14
	v_and_b32_e32 v18, 63, v162
	v_and_b32_e32 v19, 31, v18
	v_lshrrev_b32_e32 v20, 5, v18
	v_xor_b32_e32 v2, 0, v19
	v_lshlrev_b32_e32 v2, 2, v2
	v_xor_b32_e32 v3, 8, v19
	v_lshlrev_b32_e32 v3, 2, v3
	v_xor_b32_e32 v4, 16, v19
	v_lshlrev_b32_e32 v4, 2, v4
	v_xor_b32_e32 v5, 24, v19
	v_lshlrev_b32_e32 v5, 2, v5
	v_mov_b32_e32 v0, v20
	v_and_b32_e32 v19, 7, v18
	v_lshrrev_b32_e32 v20, 3, v18
	v_and_b32_e32 v21, 3, v19
	v_lshlrev_b32_e32 v22, 10, v19
	v_lshl_add_u32 v22, s5, 14, v22
	v_xor_b32_e32 v23, 0, v21
	v_lshl_add_u32 v23, v23, 3, v20
	v_lshl_add_u32 v8, v23, 2, v22
	v_xor_b32_e32 v23, 1, v21
	v_lshl_add_u32 v23, v23, 3, v20
	v_lshl_add_u32 v9, v23, 2, v22
	v_xor_b32_e32 v23, 2, v21
	v_lshl_add_u32 v23, v23, 3, v20
	v_lshl_add_u32 v10, v23, 2, v22
	v_xor_b32_e32 v23, 3, v21
	v_lshl_add_u32 v23, v23, 3, v20
	v_lshl_add_u32 v11, v23, 2, v22
	v_lshlrev_b32_e32 v23, 12, v20
	v_lshl_add_u32 v13, v19, 4, v23
	v_add_u32_e32 v14, 0x8000, v13
	v_add_u32_e32 v15, 0x10000, v13
	v_add_u32_e32 v16, 0x18000, v13
	s_mov_b32 s8, s13
	s_waitcnt vmcnt(0) lgkmcnt(0)
	v_readfirstlane_b32 s20, v128
	v_readfirstlane_b32 s21, v129
	s_mov_b32 s11, s8
	s_cmp_ge_u32 s11, 0x8080
	s_cbranch_scc1 .Lp0b_la_p0_out
	s_mul_hi_u32 s34, s11, 0x7f808
	s_mul_i32 s36, s34, 0x2020
	s_sub_u32 s11, s11, s36
	s_mul_hi_u32 s35, s11, 0xff0100
	s_mul_i32 s36, s35, 0x101
	s_sub_u32 s11, s11, s36
	s_mul_i32 s36, s34, 0x4020000
	s_mul_i32 s37, s35, 0x201000
	s_add_u32 s36, s36, s37
	s_lshl_b32 s37, s11, 7
	s_add_u32 s36, s36, s37
	s_add_u32 s22, s16, s36
	s_addc_u32 s23, s17, 0
	s_mov_b32 s26, 0x8040
	s_mov_b32 s27, 0x10080
	s_mov_b64 s[28:29], -1
	s_mov_b64 s[30:31], -1
	s_cmp_eq_u32 s11, 0x100
	s_cbranch_scc0 .Lp0b_la_p0_done
	s_mov_b32 s28, 0xffff
	s_mov_b32 s29, 0xffff
	s_mov_b32 s30, 0xffff0000
	s_mov_b32 s31, 0xffff0000
	s_branch .Lp0b_la_p0_done
.Lp0b_la_p0_out:
	s_sub_u32 s11, s11, 0x8080
	s_lshr_b32 s34, s11, 11
	s_and_b32 s11, s11, 0x7ff
	s_lshr_b32 s35, s11, 6
	s_and_b32 s11, s11, 63
	s_lshl_b32 s36, s34, 24
	s_lshl_b32 s37, s35, 19
	s_add_u32 s36, s36, s37
	s_lshl_b32 s37, s11, 7
	s_add_u32 s36, s36, s37
	s_add_u32 s22, s18, s36
	s_addc_u32 s23, s19, 0
	s_mov_b32 s26, 0x2000
	s_mov_b32 s27, 0x4000
	s_mov_b64 s[28:29], -1
	s_mov_b64 s[30:31], -1
; #define LAS __attribute__((address_space(3)))
; __device__ __forceinline__ void transpose_item(const float* W, int K, int N, bf16_t* WT, LAS float* scr, int item, int lane) {
;     const int nblk = (N + 31) / 32, kb = item / nblk, nb = item % nblk, k0 = 64 * kb, n0 = 32 * nb;
;     const int nn = n0 + (lane & 31); const bool ok = nn < N;
;     float v[32];
; #pragma unroll
;     for (int i = 0; i < 32; ++i) { const int kk = 2 * i + (lane >> 5); v[i] = ok ? W[(size_t)(k0 + kk) * N + nn] : 0.f; }
; #pragma unroll
;     for (int i = 0; i < 32; ++i) { const int kk = 2 * i + (lane >> 5); scr[kk * 33 + (lane & 31)] = v[i]; }
; __global__ void __launch_bounds__(512, 2) mega(Args a) {
;     ...
; #pragma unroll 1
;         for (int it = it0; it < itN; it += its) {
;             int r = it;
;             if (r < 4 * I_IN) { const int l = r / I_IN; r -= l * I_IN; transpose_item(((const float*)ap->in[10]) + (size_t)l * DM * DIN, DM, DIN, WSP(bf16_t, WS_WIN) + (size_t)l * DINP * DM, scr, r, lane); }
;             else { r -= 4 * I_IN; const int l = r / I_OUT; r -= l * I_OUT; transpose_item(((const float*)ap->in[16]) + (size_t)l * DM * DM, DM, DM, WSP(bf16_t, WS_WOUT) + (size_t)l * DM * DM, scr, r, lane); }
.Lp0b_la_p0_done:
	v_mad_u32_u24 v58, v0, s26, v2
	v_mad_u32_u24 v59, v0, s26, v3
	v_mad_u32_u24 v60, v0, s26, v4
	v_mad_u32_u24 v61, v0, s26, v5
	s_mov_b64 exec, s[28:29]
	s_mov_b32 m0, s10
	s_nop 0
	global_load_lds_dword v58, s[22:23]
	s_add_i32 m0, m0, 0x100
	s_add_u32 s22, s22, s27
	s_addc_u32 s23, s23, 0
	global_load_lds_dword v58, s[22:23]
	s_add_i32 m0, m0, 0x100
	s_add_u32 s22, s22, s27
	s_addc_u32 s23, s23, 0
	global_load_lds_dword v58, s[22:23]
	s_add_i32 m0, m0, 0x100
	s_add_u32 s22, s22, s27
	s_addc_u32 s23, s23, 0
	global_load_lds_dword v58, s[22:23]
	s_mov_b64 exec, s[28:29]
	s_add_i32 m0, m0, 0x100
	s_add_u32 s22, s22, s27
	s_addc_u32 s23, s23, 0
	global_load_lds_dword v59, s[22:23]
	s_add_i32 m0, m0, 0x100
	s_add_u32 s22, s22, s27
	s_addc_u32 s23, s23, 0
	global_load_lds_dword v59, s[22:23]
	s_add_i32 m0, m0, 0x100
	s_add_u32 s22, s22, s27
	s_addc_u32 s23, s23, 0
	global_load_lds_dword v59, s[22:23]
	s_add_i32 m0, m0, 0x100
	s_add_u32 s22, s22, s27
	s_addc_u32 s23, s23, 0
	global_load_lds_dword v59, s[22:23]
	s_mov_b64 exec, s[30:31]
	s_add_i32 m0, m0, 0x100
	s_add_u32 s22, s22, s27
	s_addc_u32 s23, s23, 0
	global_load_lds_dword v60, s[22:23]
	s_add_i32 m0, m0, 0x100
	s_add_u32 s22, s22, s27
	s_addc_u32 s23, s23, 0
	global_load_lds_dword v60, s[22:23]
	s_add_i32 m0, m0, 0x100
	s_add_u32 s22, s22, s27
	s_addc_u32 s23, s23, 0
	global_load_lds_dword v60, s[22:23]
	s_add_i32 m0, m0, 0x100
	s_add_u32 s22, s22, s27
	s_addc_u32 s23, s23, 0
	global_load_lds_dword v60, s[22:23]
	s_mov_b64 exec, s[30:31]
	s_add_i32 m0, m0, 0x100
	s_add_u32 s22, s22, s27
	s_addc_u32 s23, s23, 0
	global_load_lds_dword v61, s[22:23]
	s_add_i32 m0, m0, 0x100
	s_add_u32 s22, s22, s27
	s_addc_u32 s23, s23, 0
	global_load_lds_dword v61, s[22:23]
	s_add_i32 m0, m0, 0x100
	s_add_u32 s22, s22, s27
	s_addc_u32 s23, s23, 0
	global_load_lds_dword v61, s[22:23]
	s_add_i32 m0, m0, 0x100
	s_add_u32 s22, s22, s27
	s_addc_u32 s23, s23, 0
	global_load_lds_dword v61, s[22:23]
	s_mov_b64 exec, s[28:29]
	s_add_i32 m0, m0, 0x100
	s_add_u32 s22, s22, s27
	s_addc_u32 s23, s23, 0
	global_load_lds_dword v58, s[22:23]
	s_add_i32 m0, m0, 0x100
	s_add_u32 s22, s22, s27
	s_addc_u32 s23, s23, 0
	global_load_lds_dword v58, s[22:23]
	s_add_i32 m0, m0, 0x100
	s_add_u32 s22, s22, s27
	s_addc_u32 s23, s23, 0
	global_load_lds_dword v58, s[22:23]
	s_add_i32 m0, m0, 0x100
	s_add_u32 s22, s22, s27
	s_addc_u32 s23, s23, 0
	global_load_lds_dword v58, s[22:23]
	s_mov_b64 exec, s[28:29]
	s_add_i32 m0, m0, 0x100
	s_add_u32 s22, s22, s27
	s_addc_u32 s23, s23, 0
	global_load_lds_dword v59, s[22:23]
	s_add_i32 m0, m0, 0x100
	s_add_u32 s22, s22, s27
	s_addc_u32 s23, s23, 0
	global_load_lds_dword v59, s[22:23]
	s_add_i32 m0, m0, 0x100
	s_add_u32 s22, s22, s27
	s_addc_u32 s23, s23, 0
	global_load_lds_dword v59, s[22:23]
	s_add_i32 m0, m0, 0x100
	s_add_u32 s22, s22, s27
	s_addc_u32 s23, s23, 0
	global_load_lds_dword v59, s[22:23]
	s_mov_b64 exec, s[30:31]
	s_add_i32 m0, m0, 0x100
	s_add_u32 s22, s22, s27
	s_addc_u32 s23, s23, 0
	global_load_lds_dword v60, s[22:23]
	s_add_i32 m0, m0, 0x100
	s_add_u32 s22, s22, s27
	s_addc_u32 s23, s23, 0
	global_load_lds_dword v60, s[22:23]
	s_add_i32 m0, m0, 0x100
	s_add_u32 s22, s22, s27
	s_addc_u32 s23, s23, 0
	global_load_lds_dword v60, s[22:23]
	s_add_i32 m0, m0, 0x100
	s_add_u32 s22, s22, s27
	s_addc_u32 s23, s23, 0
	global_load_lds_dword v60, s[22:23]
	s_mov_b64 exec, s[30:31]
	s_add_i32 m0, m0, 0x100
	s_add_u32 s22, s22, s27
	s_addc_u32 s23, s23, 0
	global_load_lds_dword v61, s[22:23]
	s_add_i32 m0, m0, 0x100
	s_add_u32 s22, s22, s27
	s_addc_u32 s23, s23, 0
	global_load_lds_dword v61, s[22:23]
	s_add_i32 m0, m0, 0x100
	s_add_u32 s22, s22, s27
	s_addc_u32 s23, s23, 0
	global_load_lds_dword v61, s[22:23]
	s_add_i32 m0, m0, 0x100
	s_add_u32 s22, s22, s27
	s_addc_u32 s23, s23, 0
	global_load_lds_dword v61, s[22:23]
	s_mov_b64 exec, -1
	s_add_i32 s9, s8, s15
	s_cmp_lt_i32 s9, s14
	s_cbranch_scc0 .Lp0b_nopf1
	s_mov_b32 s11, s9
	s_cmp_ge_u32 s11, 0x8080
	s_cbranch_scc1 .Lp0b_la_p1_out
	s_mul_hi_u32 s34, s11, 0x7f808
	s_mul_i32 s36, s34, 0x2020
	s_sub_u32 s11, s11, s36
	s_mul_hi_u32 s35, s11, 0xff0100
	s_mul_i32 s36, s35, 0x101
	s_sub_u32 s11, s11, s36
	s_mul_i32 s36, s34, 0x4020000
	s_mul_i32 s37, s35, 0x201000
	s_add_u32 s36, s36, s37
	s_lshl_b32 s37, s11, 7
	s_add_u32 s36, s36, s37
	s_add_u32 s22, s16, s36
	s_addc_u32 s23, s17, 0
	s_mov_b32 s26, 0x8040
	s_mov_b32 s27, 0x10080
	s_mov_b64 s[28:29], -1
	s_mov_b64 s[30:31], -1
	s_cmp_eq_u32 s11, 0x100
	s_cbranch_scc0 .Lp0b_la_p1_done
	s_mov_b32 s28, 0xffff
	s_mov_b32 s29, 0xffff
	s_mov_b32 s30, 0xffff0000
	s_mov_b32 s31, 0xffff0000
	s_branch .Lp0b_la_p1_done

; #define LAS __attribute__((address_space(3)))
; __device__ __forceinline__ unsigned pk2(float lo, float hi) { return pg8::cvt_pk_bf16(lo, hi); }
; #define LDS_WAIT() asm volatile("s_waitcnt lgkmcnt(0)" ::: "memory")
; __device__ __forceinline__ void transpose_item(const float* W, int K, int N, bf16_t* WT, LAS float* scr, int item, int lane) {
;     const int nblk = (N + 31) / 32, kb = item / nblk, nb = item % nblk, k0 = 64 * kb, n0 = 32 * nb;
;     const int nn = n0 + (lane & 31); const bool ok = nn < N;
;     float v[32];
; #pragma unroll
;     for (int i = 0; i < 32; ++i) { const int kk = 2 * i + (lane >> 5); v[i] = ok ? W[(size_t)(k0 + kk) * N + nn] : 0.f; }
; #pragma unroll
;     for (int i = 0; i < 32; ++i) { const int kk = 2 * i + (lane >> 5); scr[kk * 33 + (lane & 31)] = v[i]; }
;     LDS_WAIT(); asm volatile("" ::: "memory");
;     const int c = lane & 7;
; #pragma unroll
;     for (int j = 0; j < 4; ++j) { const int n = (lane >> 3) + 8 * j; const LAS float* s = scr + (8 * c) * 33 + n;
;         u32x4 o; o.x = pk2(s[0 * 33], s[1 * 33]); o.y = pk2(s[2 * 33], s[3 * 33]); o.z = pk2(s[4 * 33], s[5 * 33]); o.w = pk2(s[6 * 33], s[7 * 33]);
;         *(u32x4*)(WT + (size_t)(n0 + n) * K + k0 + 8 * c) = o; }
; __global__ void __launch_bounds__(512, 2) mega(Args a) {
;     ...
;         for (int it = it0; it < itN; it += its) {
;             int r = it;
;             if (r < 4 * I_IN) { const int l = r / I_IN; r -= l * I_IN; transpose_item(((const float*)ap->in[10]) + (size_t)l * DM * DIN, DM, DIN, WSP(bf16_t, WS_WIN) + (size_t)l * DINP * DM, scr, r, lane); }
;             else { r -= 4 * I_IN; const int l = r / I_OUT; r -= l * I_OUT; transpose_item(((const float*)ap->in[16]) + (size_t)l * DM * DM, DM, DM, WSP(bf16_t, WS_WOUT) + (size_t)l * DM * DM, scr, r, lane); }
.Lp0b_la_p1_done:
	v_mad_u32_u24 v58, v0, s26, v2
	v_mad_u32_u24 v59, v0, s26, v3
	v_mad_u32_u24 v60, v0, s26, v4
	v_mad_u32_u24 v61, v0, s26, v5
	s_mov_b64 exec, s[28:29]
	s_xor_b32 m0, s10, 0x2000
	s_nop 0
	global_load_lds_dword v58, s[22:23]
	s_add_i32 m0, m0, 0x100
	s_add_u32 s22, s22, s27
	s_addc_u32 s23, s23, 0
	global_load_lds_dword v58, s[22:23]
	s_add_i32 m0, m0, 0x100
	s_add_u32 s22, s22, s27
	s_addc_u32 s23, s23, 0
	global_load_lds_dword v58, s[22:23]
	s_add_i32 m0, m0, 0x100
	s_add_u32 s22, s22, s27
	s_addc_u32 s23, s23, 0
	global_load_lds_dword v58, s[22:23]
	s_mov_b64 exec, s[28:29]
	s_add_i32 m0, m0, 0x100
	s_add_u32 s22, s22, s27
	s_addc_u32 s23, s23, 0
	global_load_lds_dword v59, s[22:23]
	s_add_i32 m0, m0, 0x100
	s_add_u32 s22, s22, s27
	s_addc_u32 s23, s23, 0
	global_load_lds_dword v59, s[22:23]
	s_add_i32 m0, m0, 0x100
	s_add_u32 s22, s22, s27
	s_addc_u32 s23, s23, 0
	global_load_lds_dword v59, s[22:23]
	s_add_i32 m0, m0, 0x100
	s_add_u32 s22, s22, s27
	s_addc_u32 s23, s23, 0
	global_load_lds_dword v59, s[22:23]
	s_mov_b64 exec, s[30:31]
	s_add_i32 m0, m0, 0x100
	s_add_u32 s22, s22, s27
	s_addc_u32 s23, s23, 0
	global_load_lds_dword v60, s[22:23]
	s_add_i32 m0, m0, 0x100
	s_add_u32 s22, s22, s27
	s_addc_u32 s23, s23, 0
	global_load_lds_dword v60, s[22:23]
	s_add_i32 m0, m0, 0x100
	s_add_u32 s22, s22, s27
	s_addc_u32 s23, s23, 0
	global_load_lds_dword v60, s[22:23]
	s_add_i32 m0, m0, 0x100
	s_add_u32 s22, s22, s27
	s_addc_u32 s23, s23, 0
	global_load_lds_dword v60, s[22:23]
	s_mov_b64 exec, s[30:31]
	s_add_i32 m0, m0, 0x100
	s_add_u32 s22, s22, s27
	s_addc_u32 s23, s23, 0
	global_load_lds_dword v61, s[22:23]
	s_add_i32 m0, m0, 0x100
	s_add_u32 s22, s22, s27
	s_addc_u32 s23, s23, 0
	global_load_lds_dword v61, s[22:23]
	s_add_i32 m0, m0, 0x100
	s_add_u32 s22, s22, s27
	s_addc_u32 s23, s23, 0
	global_load_lds_dword v61, s[22:23]
	s_add_i32 m0, m0, 0x100
	s_add_u32 s22, s22, s27
	s_addc_u32 s23, s23, 0
	global_load_lds_dword v61, s[22:23]
	s_mov_b64 exec, s[28:29]
	s_add_i32 m0, m0, 0x100
	s_add_u32 s22, s22, s27
	s_addc_u32 s23, s23, 0
	global_load_lds_dword v58, s[22:23]
	s_add_i32 m0, m0, 0x100
	s_add_u32 s22, s22, s27
	s_addc_u32 s23, s23, 0
	global_load_lds_dword v58, s[22:23]
	s_add_i32 m0, m0, 0x100
	s_add_u32 s22, s22, s27
	s_addc_u32 s23, s23, 0
	global_load_lds_dword v58, s[22:23]
	s_add_i32 m0, m0, 0x100
	s_add_u32 s22, s22, s27
	s_addc_u32 s23, s23, 0
	global_load_lds_dword v58, s[22:23]
	s_mov_b64 exec, s[28:29]
	s_add_i32 m0, m0, 0x100
	s_add_u32 s22, s22, s27
	s_addc_u32 s23, s23, 0
	global_load_lds_dword v59, s[22:23]
	s_add_i32 m0, m0, 0x100
	s_add_u32 s22, s22, s27
	s_addc_u32 s23, s23, 0
	global_load_lds_dword v59, s[22:23]
	s_add_i32 m0, m0, 0x100
	s_add_u32 s22, s22, s27
	s_addc_u32 s23, s23, 0
	global_load_lds_dword v59, s[22:23]
	s_add_i32 m0, m0, 0x100
	s_add_u32 s22, s22, s27
	s_addc_u32 s23, s23, 0
	global_load_lds_dword v59, s[22:23]
	s_mov_b64 exec, s[30:31]
	s_add_i32 m0, m0, 0x100
	s_add_u32 s22, s22, s27
	s_addc_u32 s23, s23, 0
	global_load_lds_dword v60, s[22:23]
	s_add_i32 m0, m0, 0x100
	s_add_u32 s22, s22, s27
	s_addc_u32 s23, s23, 0
	global_load_lds_dword v60, s[22:23]
	s_add_i32 m0, m0, 0x100
	s_add_u32 s22, s22, s27
	s_addc_u32 s23, s23, 0
	global_load_lds_dword v60, s[22:23]
	s_add_i32 m0, m0, 0x100
	s_add_u32 s22, s22, s27
	s_addc_u32 s23, s23, 0
	global_load_lds_dword v60, s[22:23]
	s_mov_b64 exec, s[30:31]
	s_add_i32 m0, m0, 0x100
	s_add_u32 s22, s22, s27
	s_addc_u32 s23, s23, 0
	global_load_lds_dword v61, s[22:23]
	s_add_i32 m0, m0, 0x100
	s_add_u32 s22, s22, s27
	s_addc_u32 s23, s23, 0
	global_load_lds_dword v61, s[22:23]
	s_add_i32 m0, m0, 0x100
	s_add_u32 s22, s22, s27
	s_addc_u32 s23, s23, 0
	global_load_lds_dword v61, s[22:23]
	s_add_i32 m0, m0, 0x100
	s_add_u32 s22, s22, s27
	s_addc_u32 s23, s23, 0
	global_load_lds_dword v61, s[22:23]
	s_mov_b64 exec, -1
.Lp0b_nopf1:
	s_add_i32 s9, s9, s15
.Lp0b_loop:
	s_mov_b32 s11, s8
	s_mov_b64 s[40:41], 0
	s_cmp_ge_u32 s11, 0x8080
	s_cbranch_scc1 .Lp0b_sa_out
	s_mul_hi_u32 s34, s11, 0x7f808
	s_mul_i32 s36, s34, 0x2020
	s_sub_u32 s11, s11, s36
	s_mul_hi_u32 s35, s11, 0xff0100
	s_mul_i32 s36, s35, 0x101
	s_sub_u32 s11, s11, s36
	s_mul_i32 s36, s34, 0x2020000
	s_cmp_eq_u32 s11, 0x100
	s_cselect_b32 s40, -1, 0
	s_mov_b32 s41, s40
	s_branch .Lp0b_sa_done
.Lp0b_sa_out:
	s_sub_u32 s11, s11, 0x8080
	s_lshr_b32 s34, s11, 11
	s_and_b32 s11, s11, 0x7ff
	s_lshr_b32 s35, s11, 6
	s_and_b32 s11, s11, 63
	s_lshl_b32 s36, s34, 23
	s_add_u32 s36, s36, 0x8200000
.Lp0b_sa_done:
	s_lshl_b32 s37, s11, 17
	s_add_u32 s36, s36, s37
	s_lshl_b32 s37, s35, 7
	s_add_u32 s36, s36, s37
	s_add_u32 s24, s20, s36
	s_addc_u32 s25, s21, 0
	s_add_i32 s36, s8, s15
	s_cmp_lt_i32 s36, s14
	s_cbranch_scc1 .Lp0b_w32
	s_waitcnt vmcnt(0)
	s_branch .Lp0b_wd

; #define LAS __attribute__((address_space(3)))
; __device__ __forceinline__ unsigned pk2(float lo, float hi) { return pg8::cvt_pk_bf16(lo, hi); }
; #define LDS_WAIT() asm volatile("s_waitcnt lgkmcnt(0)" ::: "memory")
; __device__ __forceinline__ void transpose_item(const float* W, int K, int N, bf16_t* WT, LAS float* scr, int item, int lane) {
;     ...
;     const int c = lane & 7;
; #pragma unroll
;     for (int j = 0; j < 4; ++j) { const int n = (lane >> 3) + 8 * j; const LAS float* s = scr + (8 * c) * 33 + n;
;         u32x4 o; o.x = pk2(s[0 * 33], s[1 * 33]); o.y = pk2(s[2 * 33], s[3 * 33]); o.z = pk2(s[4 * 33], s[5 * 33]); o.w = pk2(s[6 * 33], s[7 * 33]);
;         *(u32x4*)(WT + (size_t)(n0 + n) * K + k0 + 8 * c) = o; }
;     LDS_WAIT(); asm volatile("" ::: "memory");
; }
.Lp0b_wd:
	ds_read2_b32 v[18:19], v8 offset0:0 offset1:32
	ds_read2_b32 v[20:21], v8 offset0:64 offset1:96
	ds_read2_b32 v[22:23], v8 offset0:128 offset1:160
	ds_read2_b32 v[24:25], v8 offset0:192 offset1:224
	ds_read2_b32 v[26:27], v9 offset0:0 offset1:32
	ds_read2_b32 v[28:29], v9 offset0:64 offset1:96
	ds_read2_b32 v[30:31], v9 offset0:128 offset1:160
	ds_read2_b32 v[32:33], v9 offset0:192 offset1:224
	ds_read2_b32 v[34:35], v10 offset0:0 offset1:32
	ds_read2_b32 v[36:37], v10 offset0:64 offset1:96
	ds_read2_b32 v[38:39], v10 offset0:128 offset1:160
	ds_read2_b32 v[40:41], v10 offset0:192 offset1:224
	ds_read2_b32 v[42:43], v11 offset0:0 offset1:32
	ds_read2_b32 v[44:45], v11 offset0:64 offset1:96
	ds_read2_b32 v[46:47], v11 offset0:128 offset1:160
	ds_read2_b32 v[48:49], v11 offset0:192 offset1:224
	s_waitcnt lgkmcnt(12)
	v_cvt_pk_bf16_f32 v50, v18, v19
	v_cvt_pk_bf16_f32 v51, v20, v21
	v_cvt_pk_bf16_f32 v52, v22, v23
	v_cvt_pk_bf16_f32 v53, v24, v25
	global_store_dwordx4 v13, v[50:53], s[24:25]
	s_waitcnt lgkmcnt(8)
	v_cvt_pk_bf16_f32 v54, v26, v27
	v_cvt_pk_bf16_f32 v55, v28, v29
	v_cvt_pk_bf16_f32 v56, v30, v31
	v_cvt_pk_bf16_f32 v57, v32, v33
	global_store_dwordx4 v14, v[54:57], s[24:25]
	s_waitcnt lgkmcnt(4)
	v_cvt_pk_bf16_f32 v50, v34, v35
	v_cvt_pk_bf16_f32 v51, v36, v37
	v_cvt_pk_bf16_f32 v52, v38, v39
	v_cvt_pk_bf16_f32 v53, v40, v41
	v_cndmask_b32_e64 v50, v50, 0, s[40:41]
	v_cndmask_b32_e64 v51, v51, 0, s[40:41]
	v_cndmask_b32_e64 v52, v52, 0, s[40:41]
	v_cndmask_b32_e64 v53, v53, 0, s[40:41]
	global_store_dwordx4 v15, v[50:53], s[24:25]
	s_waitcnt lgkmcnt(0)
	v_cvt_pk_bf16_f32 v54, v42, v43
	v_cvt_pk_bf16_f32 v55, v44, v45
	v_cvt_pk_bf16_f32 v56, v46, v47
	v_cvt_pk_bf16_f32 v57, v48, v49
	v_cndmask_b32_e64 v54, v54, 0, s[40:41]
	v_cndmask_b32_e64 v55, v55, 0, s[40:41]
	v_cndmask_b32_e64 v56, v56, 0, s[40:41]
	v_cndmask_b32_e64 v57, v57, 0, s[40:41]
	global_store_dwordx4 v16, v[54:57], s[24:25]
	s_cmp_lt_i32 s9, s14
	s_cbranch_scc0 .Lp0b_nopf
	s_mov_b32 s11, s9
	s_cmp_ge_u32 s11, 0x8080
	s_cbranch_scc1 .Lp0b_la_lp_out
	s_mul_hi_u32 s34, s11, 0x7f808
	s_mul_i32 s36, s34, 0x2020
	s_sub_u32 s11, s11, s36
	s_mul_hi_u32 s35, s11, 0xff0100
	s_mul_i32 s36, s35, 0x101
	s_sub_u32 s11, s11, s36
	s_mul_i32 s36, s34, 0x4020000
	s_mul_i32 s37, s35, 0x201000
	s_add_u32 s36, s36, s37
	s_lshl_b32 s37, s11, 7
	s_add_u32 s36, s36, s37
	s_add_u32 s22, s16, s36
	s_addc_u32 s23, s17, 0
	s_mov_b32 s26, 0x8040
	s_mov_b32 s27, 0x10080
	s_mov_b64 s[28:29], -1
	s_mov_b64 s[30:31], -1
	s_cmp_eq_u32 s11, 0x100
	s_cbranch_scc0 .Lp0b_la_lp_done
	s_mov_b32 s28, 0xffff
	s_mov_b32 s29, 0xffff
	s_mov_b32 s30, 0xffff0000
	s_mov_b32 s31, 0xffff0000
	s_branch .Lp0b_la_lp_done

; #define LAS __attribute__((address_space(3)))
; __device__ __forceinline__ void transpose_item(const float* W, int K, int N, bf16_t* WT, LAS float* scr, int item, int lane) {
;     const int nblk = (N + 31) / 32, kb = item / nblk, nb = item % nblk, k0 = 64 * kb, n0 = 32 * nb;
;     const int nn = n0 + (lane & 31); const bool ok = nn < N;
;     float v[32];
; #pragma unroll
;     for (int i = 0; i < 32; ++i) { const int kk = 2 * i + (lane >> 5); v[i] = ok ? W[(size_t)(k0 + kk) * N + nn] : 0.f; }
; #pragma unroll
;     for (int i = 0; i < 32; ++i) { const int kk = 2 * i + (lane >> 5); scr[kk * 33 + (lane & 31)] = v[i]; }
; __global__ void __launch_bounds__(512, 2) mega(Args a) {
;     ...
; #pragma unroll 1
;         for (int it = it0; it < itN; it += its) {
;             int r = it;
;             if (r < 4 * I_IN) { const int l = r / I_IN; r -= l * I_IN; transpose_item(((const float*)ap->in[10]) + (size_t)l * DM * DIN, DM, DIN, WSP(bf16_t, WS_WIN) + (size_t)l * DINP * DM, scr, r, lane); }
;             else { r -= 4 * I_IN; const int l = r / I_OUT; r -= l * I_OUT; transpose_item(((const float*)ap->in[16]) + (size_t)l * DM * DM, DM, DM, WSP(bf16_t, WS_WOUT) + (size_t)l * DM * DM, scr, r, lane); }
;         }
.Lp0b_la_lp_done:
	v_mad_u32_u24 v58, v0, s26, v2
	v_mad_u32_u24 v59, v0, s26, v3
	v_mad_u32_u24 v60, v0, s26, v4
	v_mad_u32_u24 v61, v0, s26, v5
	s_mov_b64 exec, s[28:29]
	s_mov_b32 m0, s10
	s_nop 0
	global_load_lds_dword v58, s[22:23]
	s_add_i32 m0, m0, 0x100
	s_add_u32 s22, s22, s27
	s_addc_u32 s23, s23, 0
	global_load_lds_dword v58, s[22:23]
	s_add_i32 m0, m0, 0x100
	s_add_u32 s22, s22, s27
	s_addc_u32 s23, s23, 0
	global_load_lds_dword v58, s[22:23]
	s_add_i32 m0, m0, 0x100
	s_add_u32 s22, s22, s27
	s_addc_u32 s23, s23, 0
	global_load_lds_dword v58, s[22:23]
	s_mov_b64 exec, s[28:29]
	s_add_i32 m0, m0, 0x100
	s_add_u32 s22, s22, s27
	s_addc_u32 s23, s23, 0
	global_load_lds_dword v59, s[22:23]
	s_add_i32 m0, m0, 0x100
	s_add_u32 s22, s22, s27
	s_addc_u32 s23, s23, 0
	global_load_lds_dword v59, s[22:23]
	s_add_i32 m0, m0, 0x100
	s_add_u32 s22, s22, s27
	s_addc_u32 s23, s23, 0
	global_load_lds_dword v59, s[22:23]
	s_add_i32 m0, m0, 0x100
	s_add_u32 s22, s22, s27
	s_addc_u32 s23, s23, 0
	global_load_lds_dword v59, s[22:23]
	s_mov_b64 exec, s[30:31]
	s_add_i32 m0, m0, 0x100
	s_add_u32 s22, s22, s27
	s_addc_u32 s23, s23, 0
	global_load_lds_dword v60, s[22:23]
	s_add_i32 m0, m0, 0x100
	s_add_u32 s22, s22, s27
	s_addc_u32 s23, s23, 0
	global_load_lds_dword v60, s[22:23]
	s_add_i32 m0, m0, 0x100
	s_add_u32 s22, s22, s27
	s_addc_u32 s23, s23, 0
	global_load_lds_dword v60, s[22:23]
	s_add_i32 m0, m0, 0x100
	s_add_u32 s22, s22, s27
	s_addc_u32 s23, s23, 0
	global_load_lds_dword v60, s[22:23]
	s_mov_b64 exec, s[30:31]
	s_add_i32 m0, m0, 0x100
	s_add_u32 s22, s22, s27
	s_addc_u32 s23, s23, 0
	global_load_lds_dword v61, s[22:23]
	s_add_i32 m0, m0, 0x100
	s_add_u32 s22, s22, s27
	s_addc_u32 s23, s23, 0
	global_load_lds_dword v61, s[22:23]
	s_add_i32 m0, m0, 0x100
	s_add_u32 s22, s22, s27
	s_addc_u32 s23, s23, 0
	global_load_lds_dword v61, s[22:23]
	s_add_i32 m0, m0, 0x100
	s_add_u32 s22, s22, s27
	s_addc_u32 s23, s23, 0
	global_load_lds_dword v61, s[22:23]
	s_mov_b64 exec, s[28:29]
	s_add_i32 m0, m0, 0x100
	s_add_u32 s22, s22, s27
	s_addc_u32 s23, s23, 0
	global_load_lds_dword v58, s[22:23]
	s_add_i32 m0, m0, 0x100
	s_add_u32 s22, s22, s27
	s_addc_u32 s23, s23, 0
	global_load_lds_dword v58, s[22:23]
	s_add_i32 m0, m0, 0x100
	s_add_u32 s22, s22, s27
	s_addc_u32 s23, s23, 0
	global_load_lds_dword v58, s[22:23]
	s_add_i32 m0, m0, 0x100
	s_add_u32 s22, s22, s27
	s_addc_u32 s23, s23, 0
	global_load_lds_dword v58, s[22:23]
	s_mov_b64 exec, s[28:29]
	s_add_i32 m0, m0, 0x100
	s_add_u32 s22, s22, s27
	s_addc_u32 s23, s23, 0
	global_load_lds_dword v59, s[22:23]
	s_add_i32 m0, m0, 0x100
	s_add_u32 s22, s22, s27
	s_addc_u32 s23, s23, 0
	global_load_lds_dword v59, s[22:23]
	s_add_i32 m0, m0, 0x100
	s_add_u32 s22, s22, s27
	s_addc_u32 s23, s23, 0
	global_load_lds_dword v59, s[22:23]
	s_add_i32 m0, m0, 0x100
	s_add_u32 s22, s22, s27
	s_addc_u32 s23, s23, 0
	global_load_lds_dword v59, s[22:23]
	s_mov_b64 exec, s[30:31]
	s_add_i32 m0, m0, 0x100
	s_add_u32 s22, s22, s27
	s_addc_u32 s23, s23, 0
	global_load_lds_dword v60, s[22:23]
	s_add_i32 m0, m0, 0x100
	s_add_u32 s22, s22, s27
	s_addc_u32 s23, s23, 0
	global_load_lds_dword v60, s[22:23]
	s_add_i32 m0, m0, 0x100
	s_add_u32 s22, s22, s27
	s_addc_u32 s23, s23, 0
	global_load_lds_dword v60, s[22:23]
	s_add_i32 m0, m0, 0x100
	s_add_u32 s22, s22, s27
	s_addc_u32 s23, s23, 0
	global_load_lds_dword v60, s[22:23]
	s_mov_b64 exec, s[30:31]
	s_add_i32 m0, m0, 0x100
	s_add_u32 s22, s22, s27
	s_addc_u32 s23, s23, 0
	global_load_lds_dword v61, s[22:23]
	s_add_i32 m0, m0, 0x100
	s_add_u32 s22, s22, s27
	s_addc_u32 s23, s23, 0
	global_load_lds_dword v61, s[22:23]
	s_add_i32 m0, m0, 0x100
	s_add_u32 s22, s22, s27
	s_addc_u32 s23, s23, 0
	global_load_lds_dword v61, s[22:23]
	s_add_i32 m0, m0, 0x100
	s_add_u32 s22, s22, s27
	s_addc_u32 s23, s23, 0
	global_load_lds_dword v61, s[22:23]
	s_mov_b64 exec, -1
.Lp0b_nopf:
	s_add_i32 s9, s9, s15
	s_add_i32 s8, s8, s15
	s_xor_b32 s10, s10, 0x2000
	v_xor_b32_e32 v8, 0x2000, v8
	v_xor_b32_e32 v9, 0x2000, v9
	v_xor_b32_e32 v10, 0x2000, v10
	v_xor_b32_e32 v11, 0x2000, v11
	s_cmp_lt_i32 s8, s14
	s_cbranch_scc1 .Lp0b_loop
	s_waitcnt vmcnt(0)
